# init phase weight transposes: the next tile is requested (prefetch loads into an unread register) at the top of each iteration - the tile loop was bound by one memory round trip per 16 KB tile
# speedup vs baseline: 1.0038x; 1.0038x over previous
; DI void transpose_job(const int TID, const int BID, LAS unsigned char* lds, const float* W, int K, int Nsrc, int Npad, bf16_t* Bt, int mode, const float* kscale) {
;     ...
;     for (int t = BID; t < ntile; t += gridDim.x) {
;         const int n0 = (t / nkt) << 6, k0 = (t % nkt) << 6;
;         const int sc = srccol(mode, n0 + 4 * dq);
;         f32x4 va = {0.f, 0.f, 0.f, 0.f}, vb = va;
;         if (sc >= 0) {
;             va = *(const f32x4*)(W + (size_t)(k0 + 2 * kp) * Nsrc + sc); vb = *(const f32x4*)(W + (size_t)(k0 + 2 * kp + 1) * Nsrc + sc);
;             if (kscale) { va *= kscale[k0 + 2 * kp]; vb *= kscale[k0 + 2 * kp + 1]; }
.LBB0_824:
	s_add_i32 s7, s7, s6
	s_add_i32 s8, s8, s4
	s_cmpk_ge_i32 s8, 0x400
	s_cbranch_scc1 .Linitpf_skip_1
	s_ashr_i32 s9, s8, 31
	s_lshr_b32 s9, s9, 28
	s_add_i32 s9, s8, s9
	s_ashr_i32 s10, s9, 4
	s_lshl_b32 s9, s10, 6
	s_lshl_b32 s10, s10, 10
	s_sub_i32 s10, 0, s10
	s_cmp_lt_i32 s9, 0
	s_cbranch_scc1 .Linitpf_skip_1
	v_or_b32_e32 v0, s9, v79
	s_and_b32 s11, s9, 0x7fffff00
	v_lshlrev_b32_e32 v1, 1, v0
	v_lshrrev_b32_e32 v0, 2, v0
	v_and_or_b32 v0, v0, 36, s11
	s_add_i32 s11, s10, s7
	v_add_u32_e32 v2, s11, v11
	v_ashrrev_i32_e32 v3, 31, v2
	v_lshlrev_b64 v[4:5], 14, v[2:3]
	v_add_u32_e32 v2, 1, v2
	v_and_b32_e32 v1, 0xc0, v1
	v_readlane_b32 s36, v254, 11
	v_ashrrev_i32_e32 v3, 31, v2
	v_or3_b32 v0, v0, v1, v8
	v_readlane_b32 s37, v254, 12
	v_mov_b32_e32 v1, v169
	v_lshlrev_b64 v[2:3], 14, v[2:3]
	v_lshl_add_u64 v[4:5], s[36:37], 0, v[4:5]
	v_lshlrev_b64 v[0:1], 2, v[0:1]
	v_lshl_add_u64 v[2:3], s[36:37], 0, v[2:3]
	v_lshl_add_u64 v[4:5], v[4:5], 0, v[0:1]
	v_lshl_add_u64 v[6:7], v[2:3], 0, v[0:1]
	global_load_dwordx4 v[232:235], v[4:5], off
	s_nop 0
	global_load_dwordx4 v[236:239], v[6:7], off
.Linitpf_skip_1:
	s_sub_i32 s7, s7, s6
	s_sub_i32 s8, s8, s4
	s_ashr_i32 s9, s8, 31
	s_lshr_b32 s9, s9, 28
	s_add_i32 s9, s8, s9
	s_ashr_i32 s10, s9, 4
	s_lshl_b32 s9, s10, 6
	s_lshl_b32 s10, s10, 10
	s_sub_i32 s10, 0, s10
	s_cmp_lt_i32 s9, 0
	s_cbranch_scc0 .LBB0_822
	v_mov_b32_e32 v0, 0
	v_mov_b32_e32 v1, 0
	v_mov_b32_e32 v2, 0
	v_mov_b32_e32 v3, 0
	v_mov_b32_e32 v4, 0
	v_mov_b32_e32 v5, 0
	v_mov_b32_e32 v6, 0
	v_mov_b32_e32 v7, 0
	s_branch .LBB0_823

; DI void transpose_job(const int TID, const int BID, LAS unsigned char* lds, const float* W, int K, int Nsrc, int Npad, bf16_t* Bt, int mode, const float* kscale) {
;     ...
;     for (int t = BID; t < ntile; t += gridDim.x) {
;         const int n0 = (t / nkt) << 6, k0 = (t % nkt) << 6;
;         const int sc = srccol(mode, n0 + 4 * dq);
;         f32x4 va = {0.f, 0.f, 0.f, 0.f}, vb = va;
;         if (sc >= 0) {
;             va = *(const f32x4*)(W + (size_t)(k0 + 2 * kp) * Nsrc + sc); vb = *(const f32x4*)(W + (size_t)(k0 + 2 * kp + 1) * Nsrc + sc);
;             if (kscale) { va *= kscale[k0 + 2 * kp]; vb *= kscale[k0 + 2 * kp + 1]; }
.LBB0_829:
	s_add_i32 s7, s7, s6
	s_add_i32 s8, s8, s4
	s_cmpk_ge_i32 s8, 0x400
	s_cbranch_scc1 .Linitpf_skip_2
	s_ashr_i32 s9, s8, 31
	s_lshr_b32 s9, s9, 28
	s_add_i32 s9, s8, s9
	s_ashr_i32 s10, s9, 4
	s_lshl_b32 s9, s10, 6
	s_lshl_b32 s10, s10, 10
	s_sub_i32 s10, 0, s10
	s_cmp_lt_i32 s9, 0
	s_cbranch_scc1 .Linitpf_skip_2
	v_or_b32_e32 v0, s9, v79
	s_and_b32 s11, s9, 0x7fffff00
	v_lshlrev_b32_e32 v1, 1, v0
	v_lshrrev_b32_e32 v0, 2, v0
	v_and_or_b32 v0, v0, 36, s11
	s_add_i32 s11, s10, s7
	v_add_u32_e32 v2, s11, v11
	v_ashrrev_i32_e32 v3, 31, v2
	v_lshlrev_b64 v[4:5], 14, v[2:3]
	v_add_u32_e32 v2, 1, v2
	v_and_b32_e32 v1, 0xc0, v1
	v_ashrrev_i32_e32 v3, 31, v2
	v_or3_b32 v0, v0, v1, v8
	v_mov_b32_e32 v1, v169
	v_lshlrev_b64 v[2:3], 14, v[2:3]
	v_lshl_add_u64 v[4:5], s[16:17], 0, v[4:5]
	v_lshlrev_b64 v[0:1], 2, v[0:1]
	v_lshl_add_u64 v[2:3], s[16:17], 0, v[2:3]
	v_lshl_add_u64 v[4:5], v[4:5], 0, v[0:1]
	v_lshl_add_u64 v[6:7], v[2:3], 0, v[0:1]
	global_load_dwordx4 v[232:235], v[4:5], off
	s_nop 0
	global_load_dwordx4 v[236:239], v[6:7], off

; DI int srccol(int mode, int nidx) {
;     const int rho = nidx & 31;
;     if (mode == MODE_NAT) return nidx;
;     if (mode == MODE_P8) return (nidx & ~31) + perm32(rho);
;     if (mode == MODE_P8W) { const int tc = nidx & 255, bj = tc >> 7, wc = (tc >> 5) & 3; return (nidx & ~255) + 64 * wc + 32 * bj + perm32(rho); }
; DI void transpose_job(const int TID, const int BID, LAS unsigned char* lds, const float* W, int K, int Nsrc, int Npad, bf16_t* Bt, int mode, const float* kscale) {
;     ...
;     for (int t = BID; t < ntile; t += gridDim.x) {
;         const int n0 = (t / nkt) << 6, k0 = (t % nkt) << 6;
;         const int sc = srccol(mode, n0 + 4 * dq);
;         f32x4 va = {0.f, 0.f, 0.f, 0.f}, vb = va;
;         if (sc >= 0) {
;             va = *(const f32x4*)(W + (size_t)(k0 + 2 * kp) * Nsrc + sc); vb = *(const f32x4*)(W + (size_t)(k0 + 2 * kp + 1) * Nsrc + sc);
.LBB0_834:
	s_add_i32 s7, s7, s6
	s_add_i32 s8, s8, s4
	s_cmpk_ge_i32 s8, 0x400
	s_cbranch_scc1 .Linitpf_skip_3
	s_ashr_i32 s9, s8, 31
	s_lshr_b32 s9, s9, 28
	s_add_i32 s9, s8, s9
	s_ashr_i32 s10, s9, 4
	s_lshl_b32 s9, s10, 6
	s_lshl_b32 s10, s10, 10
	s_sub_i32 s10, 0, s10
	s_cmp_lt_i32 s9, 0
	s_cbranch_scc1 .Linitpf_skip_3
	v_or_b32_e32 v0, s9, v79
	s_and_b32 s11, s9, 0x7fffff00
	v_lshlrev_b32_e32 v1, 1, v0
	v_lshrrev_b32_e32 v0, 2, v0
	v_and_or_b32 v0, v0, 36, s11
	s_add_i32 s11, s10, s7
	v_add_u32_e32 v2, s11, v11
	v_ashrrev_i32_e32 v3, 31, v2
	v_lshlrev_b64 v[4:5], 14, v[2:3]
	v_add_u32_e32 v2, 1, v2
	v_and_b32_e32 v1, 0xc0, v1
	v_ashrrev_i32_e32 v3, 31, v2
	v_or3_b32 v0, v0, v1, v8
	v_mov_b32_e32 v1, v169
	v_lshlrev_b64 v[2:3], 14, v[2:3]
	v_lshl_add_u64 v[4:5], s[20:21], 0, v[4:5]
	v_lshlrev_b64 v[0:1], 2, v[0:1]
	v_lshl_add_u64 v[2:3], s[20:21], 0, v[2:3]
	v_lshl_add_u64 v[4:5], v[4:5], 0, v[0:1]
	v_lshl_add_u64 v[6:7], v[2:3], 0, v[0:1]
	global_load_dwordx4 v[232:235], v[4:5], off
	s_nop 0
	global_load_dwordx4 v[236:239], v[6:7], off

; DI void transpose_job(const int TID, const int BID, LAS unsigned char* lds, const float* W, int K, int Nsrc, int Npad, bf16_t* Bt, int mode, const float* kscale) {
;     ...
;     for (int t = BID; t < ntile; t += gridDim.x) {
;         const int n0 = (t / nkt) << 6, k0 = (t % nkt) << 6;
;         const int sc = srccol(mode, n0 + 4 * dq);
;         f32x4 va = {0.f, 0.f, 0.f, 0.f}, vb = va;
;         if (sc >= 0) {
;             va = *(const f32x4*)(W + (size_t)(k0 + 2 * kp) * Nsrc + sc); vb = *(const f32x4*)(W + (size_t)(k0 + 2 * kp + 1) * Nsrc + sc);
;             if (kscale) { va *= kscale[k0 + 2 * kp]; vb *= kscale[k0 + 2 * kp + 1]; }
;         }
.LBB0_839:
	s_add_i32 s5, s5, s6
	s_add_i32 s7, s7, s4
	s_cmpk_ge_i32 s7, 0x400
	s_cbranch_scc1 .Linitpf_skip_4
	s_ashr_i32 s8, s7, 31
	s_lshr_b32 s8, s8, 28
	s_add_i32 s8, s7, s8
	s_ashr_i32 s9, s8, 4
	s_lshl_b32 s8, s9, 6
	s_lshl_b32 s9, s9, 10
	s_sub_i32 s9, 0, s9
	s_cmp_lt_i32 s8, 0
	s_cbranch_scc1 .Linitpf_skip_4
	v_or_b32_e32 v0, s8, v79
	s_and_b32 s10, s8, 0x7fffff00
	v_lshlrev_b32_e32 v1, 1, v0
	v_lshrrev_b32_e32 v0, 2, v0
	v_and_or_b32 v0, v0, 36, s10
	s_add_i32 s10, s9, s5
	v_add_u32_e32 v2, s10, v11
	v_ashrrev_i32_e32 v3, 31, v2
	v_lshlrev_b64 v[4:5], 14, v[2:3]
	v_add_u32_e32 v2, 1, v2
	v_and_b32_e32 v1, 0xc0, v1
	v_ashrrev_i32_e32 v3, 31, v2
	v_or3_b32 v0, v0, v1, v8
	v_mov_b32_e32 v1, v169
	v_lshlrev_b64 v[2:3], 14, v[2:3]
	v_lshl_add_u64 v[4:5], s[12:13], 0, v[4:5]
	v_lshlrev_b64 v[0:1], 2, v[0:1]
	v_lshl_add_u64 v[2:3], s[12:13], 0, v[2:3]
	v_lshl_add_u64 v[4:5], v[4:5], 0, v[0:1]
	v_lshl_add_u64 v[6:7], v[2:3], 0, v[0:1]
	global_load_dwordx4 v[232:235], v[4:5], off
	s_nop 0
	global_load_dwordx4 v[236:239], v[6:7], off
.Linitpf_skip_4:
	s_sub_i32 s5, s5, s6
	s_sub_i32 s7, s7, s4
	s_ashr_i32 s8, s7, 31
	s_lshr_b32 s8, s8, 28
	s_add_i32 s8, s7, s8
	s_ashr_i32 s9, s8, 4
	s_lshl_b32 s8, s9, 6
	s_lshl_b32 s9, s9, 10
	s_sub_i32 s9, 0, s9
	s_cmp_lt_i32 s8, 0
	s_cbranch_scc0 .LBB0_837
	v_mov_b32_e32 v0, 0
	v_mov_b32_e32 v1, 0
	v_mov_b32_e32 v2, 0
	v_mov_b32_e32 v3, 0
	v_mov_b32_e32 v4, 0
	v_mov_b32_e32 v5, 0
	v_mov_b32_e32 v6, 0
	v_mov_b32_e32 v7, 0
	s_branch .LBB0_838

; DI int srccol(int mode, int nidx) {
;     ...
;     if (mode == MODE_GQA) {
;         const int tile = nidx >> 8, tc = nidx & 255, bj = tc >> 7, wc = (tc >> 5) & 3, n = rho >> 4, fq = (rho >> 2) & 3, j = rho & 3;
;         return 64 * (4 * tile + wc) + 32 * (fq >> 1) + 8 * (fq & 1) + 16 * bj + 4 * n + j;
;     }
; DI void transpose_job(const int TID, const int BID, LAS unsigned char* lds, const float* W, int K, int Nsrc, int Npad, bf16_t* Bt, int mode, const float* kscale) {
;     ...
;     for (int t = BID; t < ntile; t += gridDim.x) {
;         const int n0 = (t / nkt) << 6, k0 = (t % nkt) << 6;
;         const int sc = srccol(mode, n0 + 4 * dq);
;         f32x4 va = {0.f, 0.f, 0.f, 0.f}, vb = va;
;         if (sc >= 0) {
;             va = *(const f32x4*)(W + (size_t)(k0 + 2 * kp) * Nsrc + sc); vb = *(const f32x4*)(W + (size_t)(k0 + 2 * kp + 1) * Nsrc + sc);
.LBB0_865:
	s_add_i32 s16, s16, s17
	s_add_i32 s18, s18, s15
	s_cmpk_ge_i32 s18, 0x180
	s_cbranch_scc1 .Linitpf_skip_5
	s_ashr_i32 s19, s18, 31
	s_lshr_b32 s19, s19, 28
	s_add_i32 s19, s18, s19
	s_ashr_i32 s20, s19, 4
	s_lshl_b32 s19, s20, 6
	s_lshl_b32 s20, s20, 10
	s_sub_i32 s20, 0, s20
	s_cmp_lt_i32 s19, 0
	s_cbranch_scc1 .Linitpf_skip_5
	s_and_b32 s21, s19, 0x7fffff00
	v_or_b32_e32 v0, s19, v79
	s_lshr_b32 s22, s19, 3
	v_lshlrev_b32_e32 v0, 1, v0
	v_or_b32_e32 v1, s21, v21
	s_add_i32 s21, s20, s16
	v_and_b32_e32 v0, 0xc0, v0
	v_and_or_b32 v1, s22, 16, v1
	v_add_u32_e32 v6, s21, v11
	v_mov_b64_e32 v[2:3], s[0:1]
	v_or3_b32 v0, v1, v0, v17
	v_mad_i64_i32 v[4:5], s[22:23], v6, s95, v[2:3]
	v_mov_b32_e32 v1, v169
	v_add_u32_e32 v6, 1, v6
	v_lshlrev_b64 v[0:1], 2, v[0:1]
	v_mad_i64_i32 v[2:3], s[22:23], v6, s95, v[2:3]
	v_lshl_add_u64 v[4:5], v[4:5], 0, v[0:1]
	v_lshl_add_u64 v[6:7], v[2:3], 0, v[0:1]
	global_load_dwordx4 v[232:235], v[4:5], off
	s_nop 0
	global_load_dwordx4 v[236:239], v[6:7], off
.Linitpf_skip_5:
	s_sub_i32 s16, s16, s17
	s_sub_i32 s18, s18, s15
	s_ashr_i32 s19, s18, 31
	s_lshr_b32 s19, s19, 28
	s_add_i32 s19, s18, s19
	s_ashr_i32 s20, s19, 4
	s_lshl_b32 s19, s20, 6
	s_lshl_b32 s20, s20, 10
	s_sub_i32 s20, 0, s20
	s_cmp_lt_i32 s19, 0
	s_cbranch_scc0 .LBB0_863
	v_mov_b32_e32 v0, 0
	v_mov_b32_e32 v1, 0
	v_mov_b32_e32 v2, 0
	v_mov_b32_e32 v3, 0
	v_mov_b32_e32 v4, 0
	v_mov_b32_e32 v5, 0
	v_mov_b32_e32 v6, 0
	v_mov_b32_e32 v7, 0
	s_branch .LBB0_864

; DI int srccol(int mode, int nidx) {
;     const int rho = nidx & 31;
;     if (mode == MODE_NAT) return nidx;
;     if (mode == MODE_P8) return (nidx & ~31) + perm32(rho);
; DI void transpose_job(const int TID, const int BID, LAS unsigned char* lds, const float* W, int K, int Nsrc, int Npad, bf16_t* Bt, int mode, const float* kscale) {
;     ...
;     for (int t = BID; t < ntile; t += gridDim.x) {
;         const int n0 = (t / nkt) << 6, k0 = (t % nkt) << 6;
;         const int sc = srccol(mode, n0 + 4 * dq);
;         f32x4 va = {0.f, 0.f, 0.f, 0.f}, vb = va;
;         if (sc >= 0) {
;             va = *(const f32x4*)(W + (size_t)(k0 + 2 * kp) * Nsrc + sc); vb = *(const f32x4*)(W + (size_t)(k0 + 2 * kp + 1) * Nsrc + sc);
.LBB0_871:
	s_add_i32 s16, s16, s17
	s_add_i32 s18, s18, s15
	s_cmpk_ge_i32 s18, 0x100
	s_cbranch_scc1 .Linitpf_skip_6
	s_ashr_i32 s19, s18, 31
	s_lshr_b32 s19, s19, 28
	s_add_i32 s19, s18, s19
	s_ashr_i32 s20, s19, 4
	s_lshl_b32 s19, s20, 6
	s_lshl_b32 s20, s20, 10
	s_sub_i32 s20, 0, s20
	s_cmp_lt_i32 s19, 0
	s_cbranch_scc1 .Linitpf_skip_6
	s_add_i32 s21, s20, s16
	v_add_u32_e32 v2, s21, v11
	v_ashrrev_i32_e32 v3, 31, v2
	v_lshlrev_b64 v[4:5], 12, v[2:3]
	v_add_u32_e32 v2, 1, v2
	v_ashrrev_i32_e32 v3, 31, v2
	v_or_b32_e32 v0, s19, v19
	v_mov_b32_e32 v1, v169
	v_lshlrev_b64 v[2:3], 12, v[2:3]
	v_lshl_add_u64 v[4:5], s[54:55], 0, v[4:5]
	v_lshlrev_b64 v[0:1], 2, v[0:1]
	v_lshl_add_u64 v[2:3], s[54:55], 0, v[2:3]
	v_lshl_add_u64 v[4:5], v[4:5], 0, v[0:1]
	v_lshl_add_u64 v[6:7], v[2:3], 0, v[0:1]
	global_load_dwordx4 v[232:235], v[4:5], off
	s_nop 0
	global_load_dwordx4 v[236:239], v[6:7], off

; DI int srccol(int mode, int nidx) {
;     const int rho = nidx & 31;
;     if (mode == MODE_NAT) return nidx;
;     if (mode == MODE_P8) return (nidx & ~31) + perm32(rho);
; DI void transpose_job(const int TID, const int BID, LAS unsigned char* lds, const float* W, int K, int Nsrc, int Npad, bf16_t* Bt, int mode, const float* kscale) {
;     ...
;     for (int t = BID; t < ntile; t += gridDim.x) {
;         const int n0 = (t / nkt) << 6, k0 = (t % nkt) << 6;
;         const int sc = srccol(mode, n0 + 4 * dq);
;         f32x4 va = {0.f, 0.f, 0.f, 0.f}, vb = va;
;         if (sc >= 0) {
;             va = *(const f32x4*)(W + (size_t)(k0 + 2 * kp) * Nsrc + sc); vb = *(const f32x4*)(W + (size_t)(k0 + 2 * kp + 1) * Nsrc + sc);
.LBB0_898:
	s_add_i32 s16, s16, s17
	s_add_i32 s18, s18, s15
	s_cmpk_ge_i32 s18, 0x100
	s_cbranch_scc1 .Linitpf_skip_7
	s_ashr_i32 s19, s18, 31
	s_lshr_b32 s19, s19, 28
	s_add_i32 s19, s18, s19
	s_ashr_i32 s20, s19, 4
	s_lshl_b32 s19, s20, 6
	s_lshl_b32 s20, s20, 10
	s_sub_i32 s20, 0, s20
	s_cmp_lt_i32 s19, 0
	s_cbranch_scc1 .Linitpf_skip_7
	s_add_i32 s21, s20, s16
	v_add_u32_e32 v2, s21, v11
	v_ashrrev_i32_e32 v3, 31, v2
	v_lshlrev_b64 v[4:5], 12, v[2:3]
	v_add_u32_e32 v2, 1, v2
	v_ashrrev_i32_e32 v3, 31, v2
	v_or_b32_e32 v0, s19, v19
	v_mov_b32_e32 v1, v169
	v_lshlrev_b64 v[2:3], 12, v[2:3]
	v_lshl_add_u64 v[4:5], s[0:1], 0, v[4:5]
	v_lshlrev_b64 v[0:1], 2, v[0:1]
	v_lshl_add_u64 v[2:3], s[0:1], 0, v[2:3]
	v_lshl_add_u64 v[4:5], v[4:5], 0, v[0:1]
	v_lshl_add_u64 v[6:7], v[2:3], 0, v[0:1]
	global_load_dwordx4 v[232:235], v[4:5], off
	s_nop 0
	global_load_dwordx4 v[236:239], v[6:7], off
